# hand-scheduled attention main loop: LDS fragment double-buffer prefetch, softmax VALU spread under MFMAs, barrier before last PV group
# speedup vs baseline: 1.0207x; 1.0207x over previous
.LBB0_404:
	v_readfirstlane_b32 s13, v0
	s_nop 1
	v_cmp_eq_u32_e32 vcc, s13, v0
	s_and_saveexec_b64 vcc, vcc
	s_nop 0
	buffer_load_dwordx4 v205, s[28:31], s13 offen lds
	s_xor_b64 exec, exec, vcc
	s_cbranch_execnz .LBB0_404
	s_mov_b64 exec, s[10:11]
	s_mov_b32 m0, s90
	v_add_u32_e32 v175, v207, v201
	buffer_load_dwordx4 v206, s[36:39], s12 offen lds
	s_bitset1_b32 s12, 21
	s_mov_b32 m0, s91
	v_add_u32_e32 v217, v207, v202
	buffer_load_dwordx4 v206, s[36:39], s12 offen lds
	s_waitcnt vmcnt(4)
	s_barrier
	ds_read_b128 v[0:3], v175 offset:4096
	ds_read_b128 v[4:7], v175
	s_waitcnt vmcnt(15) lgkmcnt(0)
	v_mfma_f32_32x32x16_bf16 v[112:127], v[4:7], v[140:143], 0
	v_add_u32_e32 v218, v207, v203
	v_add_u32_e32 v219, v207, v204
	s_or_b32 s10, s85, 1
	s_mov_b32 s12, 0
	s_cmp_lt_u32 s1, 2
	v_mfma_f32_32x32x16_bf16 v[96:111], v[0:3], v[140:143], 0
	ds_read_b128 v[0:3], v217 offset:4096
	ds_read_b128 v[4:7], v217
	s_waitcnt vmcnt(14) lgkmcnt(0)
	v_mfma_f32_32x32x16_bf16 v[112:127], v[4:7], v[136:139], v[112:127]
	v_mfma_f32_32x32x16_bf16 v[96:111], v[0:3], v[136:139], v[96:111]
	ds_read_b128 v[0:3], v218 offset:4096
	ds_read_b128 v[4:7], v218
	s_waitcnt vmcnt(13) lgkmcnt(0)
	v_mfma_f32_32x32x16_bf16 v[112:127], v[4:7], v[132:135], v[112:127]
	v_mfma_f32_32x32x16_bf16 v[96:111], v[0:3], v[132:135], v[96:111]
	ds_read_b128 v[0:3], v219 offset:4096
	ds_read_b128 v[4:7], v219
	s_waitcnt vmcnt(12) lgkmcnt(0)
	v_mfma_f32_32x32x16_bf16 v[112:127], v[4:7], v[128:131], v[112:127]
	v_mfma_f32_32x32x16_bf16 v[96:111], v[0:3], v[128:131], v[96:111]
	s_mov_b32 s14, 0
	s_mov_b32 s15, s10
	s_mov_b32 s16, s85
	s_mov_b32 s38, s30
	s_mov_b32 s39, s31
	ds_read_b128 v[144:147], v175 offset:32768
	ds_read_b128 v[148:151], v175 offset:36864
	ds_read_b128 v[152:155], v217 offset:32768
	ds_read_b128 v[156:159], v217 offset:36864
	v_mov_b32_e32 v220, 0
	v_mov_b32_e32 v0, 0
	v_mov_b32_e32 v1, 0
	v_mov_b32_e32 v2, 0
	v_mov_b32_e32 v3, 0
	v_mov_b32_e32 v4, 0
	v_mov_b32_e32 v5, 0
	v_mov_b32_e32 v6, 0
	v_mov_b32_e32 v7, 0
	v_mov_b32_e32 v8, 0
	v_mov_b32_e32 v9, 0
	v_mov_b32_e32 v10, 0
	v_mov_b32_e32 v11, 0
	v_mov_b32_e32 v12, 0
	v_mov_b32_e32 v13, 0
	v_mov_b32_e32 v14, 0
	v_mov_b32_e32 v15, 0
	v_mov_b32_e32 v16, 0
	v_mov_b32_e32 v17, 0
	v_mov_b32_e32 v18, 0
	v_mov_b32_e32 v19, 0
	v_mov_b32_e32 v20, 0
	v_mov_b32_e32 v21, 0
	v_mov_b32_e32 v22, 0
	v_mov_b32_e32 v23, 0
	v_mov_b32_e32 v24, 0
	v_mov_b32_e32 v25, 0
	v_mov_b32_e32 v26, 0
	v_mov_b32_e32 v27, 0
	v_mov_b32_e32 v28, 0
	v_mov_b32_e32 v29, 0
	v_mov_b32_e32 v30, 0
	v_mov_b32_e32 v31, 0
	v_mov_b32_e32 v32, 0
	v_mov_b32_e32 v33, 0
	v_mov_b32_e32 v34, 0
	v_mov_b32_e32 v35, 0
	v_mov_b32_e32 v36, 0
	v_mov_b32_e32 v37, 0
	v_mov_b32_e32 v38, 0
	v_mov_b32_e32 v39, 0
	v_mov_b32_e32 v40, 0
	v_mov_b32_e32 v41, 0
	v_mov_b32_e32 v42, 0
	v_mov_b32_e32 v43, 0
	v_mov_b32_e32 v44, 0
	v_mov_b32_e32 v45, 0
	v_mov_b32_e32 v46, 0
	v_mov_b32_e32 v47, 0
	v_mov_b32_e32 v48, 0
	v_mov_b32_e32 v49, 0
	v_mov_b32_e32 v50, 0
	v_mov_b32_e32 v51, 0
	v_mov_b32_e32 v52, 0
	v_mov_b32_e32 v53, 0
	v_mov_b32_e32 v54, 0
	v_mov_b32_e32 v55, 0
	v_mov_b32_e32 v56, 0
	v_mov_b32_e32 v57, 0
	v_mov_b32_e32 v58, 0
	v_mov_b32_e32 v59, 0
	v_mov_b32_e32 v60, 0
	v_mov_b32_e32 v61, 0
	v_mov_b32_e32 v62, 0
	v_mov_b32_e32 v63, 0
	s_cmp_lt_u32 s16, 4
	s_cbranch_scc1 .Lat_rem_check
.Lat_main:
	ds_read_b128 v[224:227], v218 offset:32768
	ds_read_b128 v[228:231], v218 offset:36864
	ds_read_b128 v[232:235], v219 offset:32768
	ds_read_b128 v[236:239], v219 offset:36864
	s_waitcnt lgkmcnt(4)
	v_mfma_f32_32x32x16_bf16 v[80:95], v[144:147], v[140:143], 0
	v_exp_f32_e32 v112, v112
	v_exp_f32_e32 v113, v113
	v_add_f32_e32 v220, v220, v112
	v_cvt_pk_bf16_f32 v240, v112, v113
	v_mfma_f32_32x32x16_bf16 v[64:79], v[148:151], v[140:143], 0
	v_exp_f32_e32 v114, v114
	v_exp_f32_e32 v115, v115
	v_add_f32_e32 v220, v220, v113
	v_cvt_pk_bf16_f32 v241, v114, v115
	v_mfma_f32_32x32x16_bf16 v[80:95], v[152:155], v[136:139], v[80:95]
	v_exp_f32_e32 v116, v116
	v_exp_f32_e32 v117, v117
	v_add_f32_e32 v220, v220, v114
	v_cvt_pk_bf16_f32 v242, v116, v117
	v_mfma_f32_32x32x16_bf16 v[64:79], v[156:159], v[136:139], v[64:79]
	v_exp_f32_e32 v118, v118
	v_exp_f32_e32 v119, v119
	v_add_f32_e32 v220, v220, v115
	v_cvt_pk_bf16_f32 v243, v118, v119
	v_add_u32_e32 v221, v208, v201
	ds_read_b128 v[144:147], v221 offset:16384
	ds_read_b128 v[148:151], v221 offset:20480
	ds_read_b128 v[152:155], v221 offset:24576
	ds_read_b128 v[156:159], v221 offset:28672
	s_waitcnt lgkmcnt(4)
	v_mfma_f32_32x32x16_bf16 v[80:95], v[224:227], v[132:135], v[80:95]
	v_exp_f32_e32 v120, v120
	v_exp_f32_e32 v121, v121
	v_add_f32_e32 v220, v220, v116
	v_cvt_pk_bf16_f32 v244, v120, v121
	v_mfma_f32_32x32x16_bf16 v[64:79], v[228:231], v[132:135], v[64:79]
	v_exp_f32_e32 v122, v122
	v_exp_f32_e32 v123, v123
	v_add_f32_e32 v220, v220, v117
	v_cvt_pk_bf16_f32 v245, v122, v123
	v_mfma_f32_32x32x16_bf16 v[80:95], v[232:235], v[128:131], v[80:95]
	v_exp_f32_e32 v124, v124
	v_exp_f32_e32 v125, v125
	v_add_f32_e32 v220, v220, v118
	v_cvt_pk_bf16_f32 v246, v124, v125
	v_mfma_f32_32x32x16_bf16 v[64:79], v[236:239], v[128:131], v[64:79]
	v_exp_f32_e32 v126, v126
	v_exp_f32_e32 v127, v127
	v_add_f32_e32 v220, v220, v119
	v_cvt_pk_bf16_f32 v247, v126, v127
	v_add_u32_e32 v221, v208, v202
	ds_read_b128 v[224:227], v221 offset:16384
	ds_read_b128 v[228:231], v221 offset:20480
	ds_read_b128 v[232:235], v221 offset:24576
	ds_read_b128 v[236:239], v221 offset:28672
	s_waitcnt lgkmcnt(4)
	v_mfma_f32_32x32x16_bf16 v[48:63], v[144:147], v[240:243], v[48:63]
	v_exp_f32_e32 v96, v96
	v_exp_f32_e32 v97, v97
	v_add_f32_e32 v220, v220, v120
	v_cvt_pk_bf16_f32 v248, v96, v97
	v_mfma_f32_32x32x16_bf16 v[32:47], v[148:151], v[240:243], v[32:47]
	v_exp_f32_e32 v98, v98
	v_exp_f32_e32 v99, v99
	v_add_f32_e32 v220, v220, v121
	v_cvt_pk_bf16_f32 v249, v98, v99
	v_mfma_f32_32x32x16_bf16 v[16:31], v[152:155], v[240:243], v[16:31]
	v_exp_f32_e32 v100, v100
	v_exp_f32_e32 v101, v101
	v_add_f32_e32 v220, v220, v122
	v_cvt_pk_bf16_f32 v250, v100, v101
	v_mfma_f32_32x32x16_bf16 v[0:15], v[156:159], v[240:243], v[0:15]
	v_exp_f32_e32 v102, v102
	v_exp_f32_e32 v103, v103
	v_add_f32_e32 v220, v220, v123
	v_cvt_pk_bf16_f32 v251, v102, v103
	v_add_u32_e32 v221, v208, v203
	ds_read_b128 v[144:147], v221 offset:16384
	ds_read_b128 v[148:151], v221 offset:20480
	ds_read_b128 v[152:155], v221 offset:24576
	ds_read_b128 v[156:159], v221 offset:28672
	s_waitcnt lgkmcnt(4)
	v_mfma_f32_32x32x16_bf16 v[48:63], v[224:227], v[244:247], v[48:63]
	s_add_i32 s17, s14, 3
	s_min_u32 s17, s17, s15
	v_exp_f32_e32 v104, v104
	v_exp_f32_e32 v105, v105
	v_add_f32_e32 v220, v220, v104
	v_add_f32_e32 v220, v220, v105
	v_mfma_f32_32x32x16_bf16 v[32:47], v[228:231], v[244:247], v[32:47]
	s_mul_i32 s18, s17, 0x30000
	s_lshl_b32 s19, s17, 7
	v_exp_f32_e32 v106, v106
	v_exp_f32_e32 v107, v107
	v_add_f32_e32 v220, v220, v106
	v_add_f32_e32 v220, v220, v107
	v_mfma_f32_32x32x16_bf16 v[16:31], v[232:235], v[244:247], v[16:31]
	s_or_b32 s98, s18, 0x80
	s_add_i32 s99, s19, 0x200000
	v_exp_f32_e32 v108, v108
	v_exp_f32_e32 v109, v109
	v_cvt_pk_bf16_f32 v104, v104, v105
	v_add_f32_e32 v220, v220, v124
	v_mfma_f32_32x32x16_bf16 v[0:15], v[236:239], v[244:247], v[0:15]
	v_exp_f32_e32 v110, v110
	v_exp_f32_e32 v111, v111
	v_cvt_pk_bf16_f32 v105, v106, v107
	v_add_f32_e32 v220, v220, v125
	v_add_u32_e32 v221, v208, v204
	ds_read_b128 v[224:227], v221 offset:16384
	ds_read_b128 v[228:231], v221 offset:20480
	ds_read_b128 v[232:235], v221 offset:24576
	ds_read_b128 v[236:239], v221 offset:28672
	s_waitcnt lgkmcnt(4)
	s_mov_b32 m0, s92
	v_mfma_f32_32x32x16_bf16 v[48:63], v[144:147], v[248:251], v[48:63]
	buffer_load_dwordx4 v205, s[28:31], s18 offen lds
	v_cvt_pk_bf16_f32 v106, v108, v109
	v_cvt_pk_bf16_f32 v107, v110, v111
	s_mov_b32 m0, s93
	v_mfma_f32_32x32x16_bf16 v[32:47], v[148:151], v[248:251], v[32:47]
	buffer_load_dwordx4 v205, s[28:31], s98 offen lds
	v_add_f32_e32 v220, v220, v126
	v_add_f32_e32 v220, v220, v127
	s_mov_b32 m0, s94
	v_mfma_f32_32x32x16_bf16 v[16:31], v[152:155], v[248:251], v[16:31]
	buffer_load_dwordx4 v206, s[36:39], s19 offen lds
	v_add_f32_e32 v220, v220, v96
	v_add_f32_e32 v220, v220, v97
	s_mov_b32 m0, s95
	v_mfma_f32_32x32x16_bf16 v[0:15], v[156:159], v[248:251], v[0:15]
	buffer_load_dwordx4 v206, s[36:39], s99 offen lds
	v_add_f32_e32 v220, v220, v98
	v_add_f32_e32 v220, v220, v99
	s_waitcnt vmcnt(4) lgkmcnt(0)
	s_barrier
	v_add_u32_e32 v221, v209, v201
	v_add_u32_e32 v222, v209, v202
	ds_read_b128 v[144:147], v221
	ds_read_b128 v[148:151], v221 offset:4096
	ds_read_b128 v[152:155], v222
	ds_read_b128 v[156:159], v222 offset:4096
	v_mfma_f32_32x32x16_bf16 v[48:63], v[224:227], v[104:107], v[48:63]
	v_add_f32_e32 v220, v220, v100
	v_add_f32_e32 v220, v220, v101
	v_add_f32_e32 v220, v220, v102
	v_mfma_f32_32x32x16_bf16 v[32:47], v[228:231], v[104:107], v[32:47]
	v_add_f32_e32 v220, v220, v103
	v_add_f32_e32 v220, v220, v108
	v_add_f32_e32 v220, v220, v109
	v_mfma_f32_32x32x16_bf16 v[16:31], v[232:235], v[104:107], v[16:31]
	v_add_f32_e32 v220, v220, v110
	v_add_f32_e32 v220, v220, v111
	v_mfma_f32_32x32x16_bf16 v[0:15], v[236:239], v[104:107], v[0:15]
	v_add_u32_e32 v221, v209, v203
	v_add_u32_e32 v222, v209, v204
	ds_read_b128 v[224:227], v221
	ds_read_b128 v[228:231], v221 offset:4096
	ds_read_b128 v[232:235], v222
	ds_read_b128 v[236:239], v222 offset:4096
	s_waitcnt lgkmcnt(4)
	v_mfma_f32_32x32x16_bf16 v[112:127], v[144:147], v[140:143], 0
	v_exp_f32_e32 v80, v80
	v_exp_f32_e32 v81, v81
	v_add_f32_e32 v220, v220, v80
	v_cvt_pk_bf16_f32 v240, v80, v81
	v_mfma_f32_32x32x16_bf16 v[96:111], v[148:151], v[140:143], 0
	v_exp_f32_e32 v82, v82
	v_exp_f32_e32 v83, v83
	v_add_f32_e32 v220, v220, v81
	v_cvt_pk_bf16_f32 v241, v82, v83
	v_mfma_f32_32x32x16_bf16 v[112:127], v[152:155], v[136:139], v[112:127]
	v_exp_f32_e32 v84, v84
	v_exp_f32_e32 v85, v85
	v_add_f32_e32 v220, v220, v82
	v_cvt_pk_bf16_f32 v242, v84, v85
	v_mfma_f32_32x32x16_bf16 v[96:111], v[156:159], v[136:139], v[96:111]
	v_exp_f32_e32 v86, v86
	v_exp_f32_e32 v87, v87
	v_add_f32_e32 v220, v220, v83
	v_cvt_pk_bf16_f32 v243, v86, v87
	v_add_u32_e32 v221, v208, v201
	ds_read_b128 v[144:147], v221 offset:49152
	ds_read_b128 v[148:151], v221 offset:53248
	ds_read_b128 v[152:155], v221 offset:57344
	ds_read_b128 v[156:159], v221 offset:61440
	s_waitcnt lgkmcnt(4)
	v_mfma_f32_32x32x16_bf16 v[112:127], v[224:227], v[132:135], v[112:127]
	v_exp_f32_e32 v88, v88
	v_exp_f32_e32 v89, v89
	v_add_f32_e32 v220, v220, v84
	v_cvt_pk_bf16_f32 v244, v88, v89
	v_mfma_f32_32x32x16_bf16 v[96:111], v[228:231], v[132:135], v[96:111]
	v_exp_f32_e32 v90, v90
	v_exp_f32_e32 v91, v91
	v_add_f32_e32 v220, v220, v85
	v_cvt_pk_bf16_f32 v245, v90, v91
	v_mfma_f32_32x32x16_bf16 v[112:127], v[232:235], v[128:131], v[112:127]
	v_exp_f32_e32 v92, v92
	v_exp_f32_e32 v93, v93
	v_add_f32_e32 v220, v220, v86
	v_cvt_pk_bf16_f32 v246, v92, v93
	v_mfma_f32_32x32x16_bf16 v[96:111], v[236:239], v[128:131], v[96:111]
	v_exp_f32_e32 v94, v94
	v_exp_f32_e32 v95, v95
	v_add_f32_e32 v220, v220, v87
	v_cvt_pk_bf16_f32 v247, v94, v95
	v_add_u32_e32 v221, v208, v202
	ds_read_b128 v[224:227], v221 offset:49152
	ds_read_b128 v[228:231], v221 offset:53248
	ds_read_b128 v[232:235], v221 offset:57344
	ds_read_b128 v[236:239], v221 offset:61440
	s_waitcnt lgkmcnt(4)
	v_mfma_f32_32x32x16_bf16 v[48:63], v[144:147], v[240:243], v[48:63]
	v_exp_f32_e32 v64, v64
	v_exp_f32_e32 v65, v65
	v_add_f32_e32 v220, v220, v88
	v_cvt_pk_bf16_f32 v248, v64, v65
	v_mfma_f32_32x32x16_bf16 v[32:47], v[148:151], v[240:243], v[32:47]
	v_exp_f32_e32 v66, v66
	v_exp_f32_e32 v67, v67
	v_add_f32_e32 v220, v220, v89
	v_cvt_pk_bf16_f32 v249, v66, v67
	v_mfma_f32_32x32x16_bf16 v[16:31], v[152:155], v[240:243], v[16:31]
	v_exp_f32_e32 v68, v68
	v_exp_f32_e32 v69, v69
	v_add_f32_e32 v220, v220, v90
	v_cvt_pk_bf16_f32 v250, v68, v69
	v_mfma_f32_32x32x16_bf16 v[0:15], v[156:159], v[240:243], v[0:15]
	v_exp_f32_e32 v70, v70
	v_exp_f32_e32 v71, v71
	v_add_f32_e32 v220, v220, v91
	v_cvt_pk_bf16_f32 v251, v70, v71
	v_add_u32_e32 v221, v208, v203
	ds_read_b128 v[144:147], v221 offset:49152
	ds_read_b128 v[148:151], v221 offset:53248
	ds_read_b128 v[152:155], v221 offset:57344
	ds_read_b128 v[156:159], v221 offset:61440
	s_waitcnt lgkmcnt(4)
	v_mfma_f32_32x32x16_bf16 v[48:63], v[224:227], v[244:247], v[48:63]
	s_add_i32 s17, s14, 4
	s_min_u32 s17, s17, s15
	v_exp_f32_e32 v72, v72
	v_exp_f32_e32 v73, v73
	v_add_f32_e32 v220, v220, v72
	v_add_f32_e32 v220, v220, v73
	v_mfma_f32_32x32x16_bf16 v[32:47], v[228:231], v[244:247], v[32:47]
	s_mul_i32 s18, s17, 0x30000
	s_lshl_b32 s19, s17, 7
	v_exp_f32_e32 v74, v74
	v_exp_f32_e32 v75, v75
	v_add_f32_e32 v220, v220, v74
	v_add_f32_e32 v220, v220, v75
	v_mfma_f32_32x32x16_bf16 v[16:31], v[232:235], v[244:247], v[16:31]
	s_or_b32 s98, s18, 0x80
	s_add_i32 s99, s19, 0x200000
	v_exp_f32_e32 v76, v76
	v_exp_f32_e32 v77, v77
	v_cvt_pk_bf16_f32 v72, v72, v73
	v_add_f32_e32 v220, v220, v92
	v_mfma_f32_32x32x16_bf16 v[0:15], v[236:239], v[244:247], v[0:15]
	v_exp_f32_e32 v78, v78
	v_exp_f32_e32 v79, v79
	v_cvt_pk_bf16_f32 v73, v74, v75
	v_add_f32_e32 v220, v220, v93
	v_add_u32_e32 v221, v208, v204
	ds_read_b128 v[224:227], v221 offset:49152
	ds_read_b128 v[228:231], v221 offset:53248
	ds_read_b128 v[232:235], v221 offset:57344
	ds_read_b128 v[236:239], v221 offset:61440
	s_waitcnt lgkmcnt(4)
	s_mov_b32 m0, s72
	v_mfma_f32_32x32x16_bf16 v[48:63], v[144:147], v[248:251], v[48:63]
	buffer_load_dwordx4 v205, s[28:31], s18 offen lds
	v_cvt_pk_bf16_f32 v74, v76, v77
	v_cvt_pk_bf16_f32 v75, v78, v79
	s_mov_b32 m0, s73
	v_mfma_f32_32x32x16_bf16 v[32:47], v[148:151], v[248:251], v[32:47]
	buffer_load_dwordx4 v205, s[28:31], s98 offen lds
	v_add_f32_e32 v220, v220, v94
	v_add_f32_e32 v220, v220, v95
	s_mov_b32 m0, s6
	v_mfma_f32_32x32x16_bf16 v[16:31], v[152:155], v[248:251], v[16:31]
	buffer_load_dwordx4 v206, s[36:39], s19 offen lds
	v_add_f32_e32 v220, v220, v64
	v_add_f32_e32 v220, v220, v65
	s_mov_b32 m0, s7
	v_mfma_f32_32x32x16_bf16 v[0:15], v[156:159], v[248:251], v[0:15]
	buffer_load_dwordx4 v206, s[36:39], s99 offen lds
	v_add_f32_e32 v220, v220, v66
	v_add_f32_e32 v220, v220, v67
	s_waitcnt vmcnt(4) lgkmcnt(0)
	s_barrier
	v_add_u32_e32 v221, v210, v201
	v_add_u32_e32 v222, v210, v202
	ds_read_b128 v[144:147], v221
	ds_read_b128 v[148:151], v221 offset:4096
	ds_read_b128 v[152:155], v222
	ds_read_b128 v[156:159], v222 offset:4096
	v_mfma_f32_32x32x16_bf16 v[48:63], v[224:227], v[72:75], v[48:63]
	v_add_f32_e32 v220, v220, v68
	v_add_f32_e32 v220, v220, v69
	v_add_f32_e32 v220, v220, v70
	v_mfma_f32_32x32x16_bf16 v[32:47], v[228:231], v[72:75], v[32:47]
	v_add_f32_e32 v220, v220, v71
	v_add_f32_e32 v220, v220, v76
	v_add_f32_e32 v220, v220, v77
	v_mfma_f32_32x32x16_bf16 v[16:31], v[232:235], v[72:75], v[16:31]
	v_add_f32_e32 v220, v220, v78
	v_add_f32_e32 v220, v220, v79
	v_mfma_f32_32x32x16_bf16 v[0:15], v[236:239], v[72:75], v[0:15]
	v_add_u32_e32 v221, v210, v203
	v_add_u32_e32 v222, v210, v204
	ds_read_b128 v[224:227], v221
	ds_read_b128 v[228:231], v221 offset:4096
	ds_read_b128 v[232:235], v222
	ds_read_b128 v[236:239], v222 offset:4096
	s_waitcnt lgkmcnt(4)
	v_mfma_f32_32x32x16_bf16 v[80:95], v[144:147], v[140:143], 0
	v_exp_f32_e32 v112, v112
	v_exp_f32_e32 v113, v113
	v_add_f32_e32 v220, v220, v112
	v_cvt_pk_bf16_f32 v240, v112, v113
	v_mfma_f32_32x32x16_bf16 v[64:79], v[148:151], v[140:143], 0
	v_exp_f32_e32 v114, v114
	v_exp_f32_e32 v115, v115
	v_add_f32_e32 v220, v220, v113
	v_cvt_pk_bf16_f32 v241, v114, v115
	v_mfma_f32_32x32x16_bf16 v[80:95], v[152:155], v[136:139], v[80:95]
	v_exp_f32_e32 v116, v116
	v_exp_f32_e32 v117, v117
	v_add_f32_e32 v220, v220, v114
	v_cvt_pk_bf16_f32 v242, v116, v117
	v_mfma_f32_32x32x16_bf16 v[64:79], v[156:159], v[136:139], v[64:79]
	v_exp_f32_e32 v118, v118
	v_exp_f32_e32 v119, v119
	v_add_f32_e32 v220, v220, v115
	v_cvt_pk_bf16_f32 v243, v118, v119
	v_add_u32_e32 v221, v211, v201
	ds_read_b128 v[144:147], v221
	ds_read_b128 v[148:151], v221 offset:4096
	ds_read_b128 v[152:155], v221 offset:8192
	ds_read_b128 v[156:159], v221 offset:12288
	s_waitcnt lgkmcnt(4)
	v_mfma_f32_32x32x16_bf16 v[80:95], v[224:227], v[132:135], v[80:95]
	v_exp_f32_e32 v120, v120
	v_exp_f32_e32 v121, v121
	v_add_f32_e32 v220, v220, v116
	v_cvt_pk_bf16_f32 v244, v120, v121
	v_mfma_f32_32x32x16_bf16 v[64:79], v[228:231], v[132:135], v[64:79]
	v_exp_f32_e32 v122, v122
	v_exp_f32_e32 v123, v123
	v_add_f32_e32 v220, v220, v117
	v_cvt_pk_bf16_f32 v245, v122, v123
	v_mfma_f32_32x32x16_bf16 v[80:95], v[232:235], v[128:131], v[80:95]
	v_exp_f32_e32 v124, v124
	v_exp_f32_e32 v125, v125
	v_add_f32_e32 v220, v220, v118
	v_cvt_pk_bf16_f32 v246, v124, v125
	v_mfma_f32_32x32x16_bf16 v[64:79], v[236:239], v[128:131], v[64:79]
	v_exp_f32_e32 v126, v126
	v_exp_f32_e32 v127, v127
	v_add_f32_e32 v220, v220, v119
	v_cvt_pk_bf16_f32 v247, v126, v127
	v_add_u32_e32 v221, v211, v202
	ds_read_b128 v[224:227], v221
	ds_read_b128 v[228:231], v221 offset:4096
	ds_read_b128 v[232:235], v221 offset:8192
	ds_read_b128 v[236:239], v221 offset:12288
	s_waitcnt lgkmcnt(4)
	v_mfma_f32_32x32x16_bf16 v[48:63], v[144:147], v[240:243], v[48:63]
	v_exp_f32_e32 v96, v96
	v_exp_f32_e32 v97, v97
	v_add_f32_e32 v220, v220, v120
	v_cvt_pk_bf16_f32 v248, v96, v97
	v_mfma_f32_32x32x16_bf16 v[32:47], v[148:151], v[240:243], v[32:47]
	v_exp_f32_e32 v98, v98
	v_exp_f32_e32 v99, v99
	v_add_f32_e32 v220, v220, v121
	v_cvt_pk_bf16_f32 v249, v98, v99
	v_mfma_f32_32x32x16_bf16 v[16:31], v[152:155], v[240:243], v[16:31]
	v_exp_f32_e32 v100, v100
	v_exp_f32_e32 v101, v101
	v_add_f32_e32 v220, v220, v122
	v_cvt_pk_bf16_f32 v250, v100, v101
	v_mfma_f32_32x32x16_bf16 v[0:15], v[156:159], v[240:243], v[0:15]
	v_exp_f32_e32 v102, v102
	v_exp_f32_e32 v103, v103
	v_add_f32_e32 v220, v220, v123
	v_cvt_pk_bf16_f32 v251, v102, v103
	v_add_u32_e32 v221, v211, v203
	ds_read_b128 v[144:147], v221
	ds_read_b128 v[148:151], v221 offset:4096
	ds_read_b128 v[152:155], v221 offset:8192
	ds_read_b128 v[156:159], v221 offset:12288
	s_waitcnt lgkmcnt(4)
	v_mfma_f32_32x32x16_bf16 v[48:63], v[224:227], v[244:247], v[48:63]
	s_add_i32 s17, s14, 5
	s_min_u32 s17, s17, s15
	v_exp_f32_e32 v104, v104
	v_exp_f32_e32 v105, v105
	v_add_f32_e32 v220, v220, v104
	v_add_f32_e32 v220, v220, v105
	v_mfma_f32_32x32x16_bf16 v[32:47], v[228:231], v[244:247], v[32:47]
	s_mul_i32 s18, s17, 0x30000
	s_lshl_b32 s19, s17, 7
	v_exp_f32_e32 v106, v106
	v_exp_f32_e32 v107, v107
	v_add_f32_e32 v220, v220, v106
	v_add_f32_e32 v220, v220, v107
	v_mfma_f32_32x32x16_bf16 v[16:31], v[232:235], v[244:247], v[16:31]
	s_or_b32 s98, s18, 0x80
	s_add_i32 s99, s19, 0x200000
	v_exp_f32_e32 v108, v108
	v_exp_f32_e32 v109, v109
	v_cvt_pk_bf16_f32 v104, v104, v105
	v_add_f32_e32 v220, v220, v124
	v_mfma_f32_32x32x16_bf16 v[0:15], v[236:239], v[244:247], v[0:15]
	v_exp_f32_e32 v110, v110
	v_exp_f32_e32 v111, v111
	v_cvt_pk_bf16_f32 v105, v106, v107
	v_add_f32_e32 v220, v220, v125
	v_add_u32_e32 v221, v211, v204
	ds_read_b128 v[224:227], v221
	ds_read_b128 v[228:231], v221 offset:4096
	ds_read_b128 v[232:235], v221 offset:8192
	ds_read_b128 v[236:239], v221 offset:12288
	s_waitcnt lgkmcnt(4)
	s_mov_b32 m0, s8
	v_mfma_f32_32x32x16_bf16 v[48:63], v[144:147], v[248:251], v[48:63]
	buffer_load_dwordx4 v205, s[28:31], s18 offen lds
	v_cvt_pk_bf16_f32 v106, v108, v109
	v_cvt_pk_bf16_f32 v107, v110, v111
	s_mov_b32 m0, s9
	v_mfma_f32_32x32x16_bf16 v[32:47], v[148:151], v[248:251], v[32:47]
	buffer_load_dwordx4 v205, s[28:31], s98 offen lds
	v_add_f32_e32 v220, v220, v126
	v_add_f32_e32 v220, v220, v127
	s_mov_b32 m0, s58
	v_mfma_f32_32x32x16_bf16 v[16:31], v[152:155], v[248:251], v[16:31]
	buffer_load_dwordx4 v206, s[36:39], s19 offen lds
	v_add_f32_e32 v220, v220, v96
	v_add_f32_e32 v220, v220, v97
	s_mov_b32 m0, s79
	v_mfma_f32_32x32x16_bf16 v[0:15], v[156:159], v[248:251], v[0:15]
	buffer_load_dwordx4 v206, s[36:39], s99 offen lds
	v_add_f32_e32 v220, v220, v98
	v_add_f32_e32 v220, v220, v99
	s_waitcnt vmcnt(4) lgkmcnt(0)
	s_barrier
	ds_read_b128 v[144:147], v175
	ds_read_b128 v[148:151], v175 offset:4096
	ds_read_b128 v[152:155], v217
	ds_read_b128 v[156:159], v217 offset:4096
	v_mfma_f32_32x32x16_bf16 v[48:63], v[224:227], v[104:107], v[48:63]
	v_add_f32_e32 v220, v220, v100
	v_add_f32_e32 v220, v220, v101
	v_add_f32_e32 v220, v220, v102
	v_mfma_f32_32x32x16_bf16 v[32:47], v[228:231], v[104:107], v[32:47]
	v_add_f32_e32 v220, v220, v103
	v_add_f32_e32 v220, v220, v108
	v_add_f32_e32 v220, v220, v109
	v_mfma_f32_32x32x16_bf16 v[16:31], v[232:235], v[104:107], v[16:31]
	v_add_f32_e32 v220, v220, v110
	v_add_f32_e32 v220, v220, v111
	v_mfma_f32_32x32x16_bf16 v[0:15], v[236:239], v[104:107], v[0:15]
	ds_read_b128 v[224:227], v218
	ds_read_b128 v[228:231], v218 offset:4096
	ds_read_b128 v[232:235], v219
	ds_read_b128 v[236:239], v219 offset:4096
	s_waitcnt lgkmcnt(4)
	v_mfma_f32_32x32x16_bf16 v[112:127], v[144:147], v[140:143], 0
	v_exp_f32_e32 v80, v80
	v_exp_f32_e32 v81, v81
	v_add_f32_e32 v220, v220, v80
	v_cvt_pk_bf16_f32 v240, v80, v81
	v_mfma_f32_32x32x16_bf16 v[96:111], v[148:151], v[140:143], 0
	v_exp_f32_e32 v82, v82
	v_exp_f32_e32 v83, v83
	v_add_f32_e32 v220, v220, v81
	v_cvt_pk_bf16_f32 v241, v82, v83
	v_mfma_f32_32x32x16_bf16 v[112:127], v[152:155], v[136:139], v[112:127]
	v_exp_f32_e32 v84, v84
	v_exp_f32_e32 v85, v85
	v_add_f32_e32 v220, v220, v82
	v_cvt_pk_bf16_f32 v242, v84, v85
	v_mfma_f32_32x32x16_bf16 v[96:111], v[156:159], v[136:139], v[96:111]
	v_exp_f32_e32 v86, v86
	v_exp_f32_e32 v87, v87
	v_add_f32_e32 v220, v220, v83
	v_cvt_pk_bf16_f32 v243, v86, v87
	v_add_u32_e32 v221, v212, v201
	ds_read_b128 v[144:147], v221
	ds_read_b128 v[148:151], v221 offset:4096
	ds_read_b128 v[152:155], v221 offset:8192
	ds_read_b128 v[156:159], v221 offset:12288
	s_waitcnt lgkmcnt(4)
	v_mfma_f32_32x32x16_bf16 v[112:127], v[224:227], v[132:135], v[112:127]
	v_exp_f32_e32 v88, v88
	v_exp_f32_e32 v89, v89
	v_add_f32_e32 v220, v220, v84
	v_cvt_pk_bf16_f32 v244, v88, v89
	v_mfma_f32_32x32x16_bf16 v[96:111], v[228:231], v[132:135], v[96:111]
	v_exp_f32_e32 v90, v90
	v_exp_f32_e32 v91, v91
	v_add_f32_e32 v220, v220, v85
	v_cvt_pk_bf16_f32 v245, v90, v91
	v_mfma_f32_32x32x16_bf16 v[112:127], v[232:235], v[128:131], v[112:127]
	v_exp_f32_e32 v92, v92
	v_exp_f32_e32 v93, v93
	v_add_f32_e32 v220, v220, v86
	v_cvt_pk_bf16_f32 v246, v92, v93
	v_mfma_f32_32x32x16_bf16 v[96:111], v[236:239], v[128:131], v[96:111]
	v_exp_f32_e32 v94, v94
	v_exp_f32_e32 v95, v95
	v_add_f32_e32 v220, v220, v87
	v_cvt_pk_bf16_f32 v247, v94, v95
	v_add_u32_e32 v221, v212, v202
	ds_read_b128 v[224:227], v221
	ds_read_b128 v[228:231], v221 offset:4096
	ds_read_b128 v[232:235], v221 offset:8192
	ds_read_b128 v[236:239], v221 offset:12288
	s_waitcnt lgkmcnt(4)
	v_mfma_f32_32x32x16_bf16 v[48:63], v[144:147], v[240:243], v[48:63]
	v_exp_f32_e32 v64, v64
	v_exp_f32_e32 v65, v65
	v_add_f32_e32 v220, v220, v88
	v_cvt_pk_bf16_f32 v248, v64, v65
	v_mfma_f32_32x32x16_bf16 v[32:47], v[148:151], v[240:243], v[32:47]
	v_exp_f32_e32 v66, v66
	v_exp_f32_e32 v67, v67
	v_add_f32_e32 v220, v220, v89
	v_cvt_pk_bf16_f32 v249, v66, v67
	v_mfma_f32_32x32x16_bf16 v[16:31], v[152:155], v[240:243], v[16:31]
	v_exp_f32_e32 v68, v68
	v_exp_f32_e32 v69, v69
	v_add_f32_e32 v220, v220, v90
	v_cvt_pk_bf16_f32 v250, v68, v69
	v_mfma_f32_32x32x16_bf16 v[0:15], v[156:159], v[240:243], v[0:15]
	v_exp_f32_e32 v70, v70
	v_exp_f32_e32 v71, v71
	v_add_f32_e32 v220, v220, v91
	v_cvt_pk_bf16_f32 v251, v70, v71
	v_add_u32_e32 v221, v212, v203
	ds_read_b128 v[144:147], v221
	ds_read_b128 v[148:151], v221 offset:4096
	ds_read_b128 v[152:155], v221 offset:8192
	ds_read_b128 v[156:159], v221 offset:12288
	s_waitcnt lgkmcnt(4)
	v_mfma_f32_32x32x16_bf16 v[48:63], v[224:227], v[244:247], v[48:63]
	s_add_i32 s17, s14, 6
	s_min_u32 s17, s17, s15
	v_exp_f32_e32 v72, v72
	v_exp_f32_e32 v73, v73
	v_add_f32_e32 v220, v220, v72
	v_add_f32_e32 v220, v220, v73
	v_mfma_f32_32x32x16_bf16 v[32:47], v[228:231], v[244:247], v[32:47]
	s_mul_i32 s18, s17, 0x30000
	s_lshl_b32 s19, s17, 7
	v_exp_f32_e32 v74, v74
	v_exp_f32_e32 v75, v75
	v_add_f32_e32 v220, v220, v74
	v_add_f32_e32 v220, v220, v75
	v_mfma_f32_32x32x16_bf16 v[16:31], v[232:235], v[244:247], v[16:31]
	s_or_b32 s98, s18, 0x80
	s_add_i32 s99, s19, 0x200000
	v_exp_f32_e32 v76, v76
	v_exp_f32_e32 v77, v77
	v_cvt_pk_bf16_f32 v72, v72, v73
	v_add_f32_e32 v220, v220, v92
	v_mfma_f32_32x32x16_bf16 v[0:15], v[236:239], v[244:247], v[0:15]
	v_exp_f32_e32 v78, v78
	v_exp_f32_e32 v79, v79
	v_cvt_pk_bf16_f32 v73, v74, v75
	v_add_f32_e32 v220, v220, v93
	v_add_u32_e32 v221, v212, v204
	ds_read_b128 v[224:227], v221
	ds_read_b128 v[228:231], v221 offset:4096
	ds_read_b128 v[232:235], v221 offset:8192
	ds_read_b128 v[236:239], v221 offset:12288
	s_waitcnt lgkmcnt(4)
	s_mov_b32 m0, s52
	v_mfma_f32_32x32x16_bf16 v[48:63], v[144:147], v[248:251], v[48:63]
	buffer_load_dwordx4 v205, s[28:31], s18 offen lds
	v_cvt_pk_bf16_f32 v74, v76, v77
	v_cvt_pk_bf16_f32 v75, v78, v79
	s_mov_b32 m0, s53
	v_mfma_f32_32x32x16_bf16 v[32:47], v[148:151], v[248:251], v[32:47]
	buffer_load_dwordx4 v205, s[28:31], s98 offen lds
	v_add_f32_e32 v220, v220, v94
	v_add_f32_e32 v220, v220, v95
	s_mov_b32 m0, s90
	v_mfma_f32_32x32x16_bf16 v[16:31], v[152:155], v[248:251], v[16:31]
	buffer_load_dwordx4 v206, s[36:39], s19 offen lds
	v_add_f32_e32 v220, v220, v64
	v_add_f32_e32 v220, v220, v65
	s_mov_b32 m0, s91
	v_mfma_f32_32x32x16_bf16 v[0:15], v[156:159], v[248:251], v[0:15]
	buffer_load_dwordx4 v206, s[36:39], s99 offen lds
	v_add_f32_e32 v220, v220, v66
	v_add_f32_e32 v220, v220, v67
	s_waitcnt vmcnt(4) lgkmcnt(0)
	s_barrier
	ds_read_b128 v[144:147], v175 offset:32768
	ds_read_b128 v[148:151], v175 offset:36864
	ds_read_b128 v[152:155], v217 offset:32768
	ds_read_b128 v[156:159], v217 offset:36864
	v_mfma_f32_32x32x16_bf16 v[48:63], v[224:227], v[72:75], v[48:63]
	v_add_f32_e32 v220, v220, v68
	v_add_f32_e32 v220, v220, v69
	v_add_f32_e32 v220, v220, v70
	v_mfma_f32_32x32x16_bf16 v[32:47], v[228:231], v[72:75], v[32:47]
	v_add_f32_e32 v220, v220, v71
	v_add_f32_e32 v220, v220, v76
	v_add_f32_e32 v220, v220, v77
	v_mfma_f32_32x32x16_bf16 v[16:31], v[232:235], v[72:75], v[16:31]
	v_add_f32_e32 v220, v220, v78
	v_add_f32_e32 v220, v220, v79
	v_mfma_f32_32x32x16_bf16 v[0:15], v[236:239], v[72:75], v[0:15]
	s_add_i32 s14, s14, 4
	s_add_i32 s17, s14, 4
	s_cmp_le_u32 s17, s16
	s_cbranch_scc1 .Lat_main
.Lat_rem_check:
	s_cmp_ge_u32 s14, s16
	s_cbranch_scc1 .Lat_exit
	ds_read_b128 v[224:227], v218 offset:32768
	ds_read_b128 v[228:231], v218 offset:36864
	ds_read_b128 v[232:235], v219 offset:32768
	ds_read_b128 v[236:239], v219 offset:36864
	s_waitcnt lgkmcnt(4)
	v_mfma_f32_32x32x16_bf16 v[80:95], v[144:147], v[140:143], 0
	v_exp_f32_e32 v112, v112
	v_exp_f32_e32 v113, v113
	v_add_f32_e32 v220, v220, v112
	v_cvt_pk_bf16_f32 v240, v112, v113
	v_mfma_f32_32x32x16_bf16 v[64:79], v[148:151], v[140:143], 0
	v_exp_f32_e32 v114, v114
	v_exp_f32_e32 v115, v115
	v_add_f32_e32 v220, v220, v113
	v_cvt_pk_bf16_f32 v241, v114, v115
	v_mfma_f32_32x32x16_bf16 v[80:95], v[152:155], v[136:139], v[80:95]
	v_exp_f32_e32 v116, v116
	v_exp_f32_e32 v117, v117
	v_add_f32_e32 v220, v220, v114
	v_cvt_pk_bf16_f32 v242, v116, v117
	v_mfma_f32_32x32x16_bf16 v[64:79], v[156:159], v[136:139], v[64:79]
	v_exp_f32_e32 v118, v118
	v_exp_f32_e32 v119, v119
	v_add_f32_e32 v220, v220, v115
	v_cvt_pk_bf16_f32 v243, v118, v119
	v_add_u32_e32 v221, v208, v201
	ds_read_b128 v[144:147], v221 offset:16384
	ds_read_b128 v[148:151], v221 offset:20480
	ds_read_b128 v[152:155], v221 offset:24576
	ds_read_b128 v[156:159], v221 offset:28672
	s_waitcnt lgkmcnt(4)
	v_mfma_f32_32x32x16_bf16 v[80:95], v[224:227], v[132:135], v[80:95]
	v_exp_f32_e32 v120, v120
	v_exp_f32_e32 v121, v121
	v_add_f32_e32 v220, v220, v116
	v_cvt_pk_bf16_f32 v244, v120, v121
	v_mfma_f32_32x32x16_bf16 v[64:79], v[228:231], v[132:135], v[64:79]
	v_exp_f32_e32 v122, v122
	v_exp_f32_e32 v123, v123
	v_add_f32_e32 v220, v220, v117
	v_cvt_pk_bf16_f32 v245, v122, v123
	v_mfma_f32_32x32x16_bf16 v[80:95], v[232:235], v[128:131], v[80:95]
	v_exp_f32_e32 v124, v124
	v_exp_f32_e32 v125, v125
	v_add_f32_e32 v220, v220, v118
	v_cvt_pk_bf16_f32 v246, v124, v125
	v_mfma_f32_32x32x16_bf16 v[64:79], v[236:239], v[128:131], v[64:79]
	v_exp_f32_e32 v126, v126
	v_exp_f32_e32 v127, v127
	v_add_f32_e32 v220, v220, v119
	v_cvt_pk_bf16_f32 v247, v126, v127
	v_add_u32_e32 v221, v208, v202
	ds_read_b128 v[224:227], v221 offset:16384
	ds_read_b128 v[228:231], v221 offset:20480
	ds_read_b128 v[232:235], v221 offset:24576
	ds_read_b128 v[236:239], v221 offset:28672
	s_waitcnt lgkmcnt(4)
	v_mfma_f32_32x32x16_bf16 v[48:63], v[144:147], v[240:243], v[48:63]
	v_exp_f32_e32 v96, v96
	v_exp_f32_e32 v97, v97
	v_add_f32_e32 v220, v220, v120
	v_cvt_pk_bf16_f32 v248, v96, v97
	v_mfma_f32_32x32x16_bf16 v[32:47], v[148:151], v[240:243], v[32:47]
	v_exp_f32_e32 v98, v98
	v_exp_f32_e32 v99, v99
	v_add_f32_e32 v220, v220, v121
	v_cvt_pk_bf16_f32 v249, v98, v99
	v_mfma_f32_32x32x16_bf16 v[16:31], v[152:155], v[240:243], v[16:31]
	v_exp_f32_e32 v100, v100
	v_exp_f32_e32 v101, v101
	v_add_f32_e32 v220, v220, v122
	v_cvt_pk_bf16_f32 v250, v100, v101
	v_mfma_f32_32x32x16_bf16 v[0:15], v[156:159], v[240:243], v[0:15]
	v_exp_f32_e32 v102, v102
	v_exp_f32_e32 v103, v103
	v_add_f32_e32 v220, v220, v123
	v_cvt_pk_bf16_f32 v251, v102, v103
	v_add_u32_e32 v221, v208, v203
	ds_read_b128 v[144:147], v221 offset:16384
	ds_read_b128 v[148:151], v221 offset:20480
	ds_read_b128 v[152:155], v221 offset:24576
	ds_read_b128 v[156:159], v221 offset:28672
	s_waitcnt lgkmcnt(4)
	v_mfma_f32_32x32x16_bf16 v[48:63], v[224:227], v[244:247], v[48:63]
	s_add_i32 s17, s14, 3
	s_min_u32 s17, s17, s15
	v_exp_f32_e32 v104, v104
	v_exp_f32_e32 v105, v105
	v_add_f32_e32 v220, v220, v104
	v_add_f32_e32 v220, v220, v105
	v_mfma_f32_32x32x16_bf16 v[32:47], v[228:231], v[244:247], v[32:47]
	s_mul_i32 s18, s17, 0x30000
	s_lshl_b32 s19, s17, 7
	v_exp_f32_e32 v106, v106
	v_exp_f32_e32 v107, v107
	v_add_f32_e32 v220, v220, v106
	v_add_f32_e32 v220, v220, v107
	v_mfma_f32_32x32x16_bf16 v[16:31], v[232:235], v[244:247], v[16:31]
	s_or_b32 s98, s18, 0x80
	s_add_i32 s99, s19, 0x200000
	v_exp_f32_e32 v108, v108
	v_exp_f32_e32 v109, v109
	v_cvt_pk_bf16_f32 v104, v104, v105
	v_add_f32_e32 v220, v220, v124
	v_mfma_f32_32x32x16_bf16 v[0:15], v[236:239], v[244:247], v[0:15]
	v_exp_f32_e32 v110, v110
	v_exp_f32_e32 v111, v111
	v_cvt_pk_bf16_f32 v105, v106, v107
	v_add_f32_e32 v220, v220, v125
	v_add_u32_e32 v221, v208, v204
	ds_read_b128 v[224:227], v221 offset:16384
	ds_read_b128 v[228:231], v221 offset:20480
	ds_read_b128 v[232:235], v221 offset:24576
	ds_read_b128 v[236:239], v221 offset:28672
	s_waitcnt lgkmcnt(4)
	s_mov_b32 m0, s92
	v_mfma_f32_32x32x16_bf16 v[48:63], v[144:147], v[248:251], v[48:63]
	buffer_load_dwordx4 v205, s[28:31], s18 offen lds
	v_cvt_pk_bf16_f32 v106, v108, v109
	v_cvt_pk_bf16_f32 v107, v110, v111
	s_mov_b32 m0, s93
	v_mfma_f32_32x32x16_bf16 v[32:47], v[148:151], v[248:251], v[32:47]
	buffer_load_dwordx4 v205, s[28:31], s98 offen lds
	v_add_f32_e32 v220, v220, v126
	v_add_f32_e32 v220, v220, v127
	s_mov_b32 m0, s94
	v_mfma_f32_32x32x16_bf16 v[16:31], v[152:155], v[248:251], v[16:31]
	buffer_load_dwordx4 v206, s[36:39], s19 offen lds
	v_add_f32_e32 v220, v220, v96
	v_add_f32_e32 v220, v220, v97
	s_mov_b32 m0, s95
	v_mfma_f32_32x32x16_bf16 v[0:15], v[156:159], v[248:251], v[0:15]
	buffer_load_dwordx4 v206, s[36:39], s99 offen lds
	v_add_f32_e32 v220, v220, v98
	v_add_f32_e32 v220, v220, v99
	s_waitcnt vmcnt(4) lgkmcnt(0)
	s_barrier
	v_add_u32_e32 v221, v209, v201
	v_add_u32_e32 v222, v209, v202
	ds_read_b128 v[144:147], v221
	ds_read_b128 v[148:151], v221 offset:4096
	ds_read_b128 v[152:155], v222
	ds_read_b128 v[156:159], v222 offset:4096
	v_mfma_f32_32x32x16_bf16 v[48:63], v[224:227], v[104:107], v[48:63]
	v_add_f32_e32 v220, v220, v100
	v_add_f32_e32 v220, v220, v101
	v_add_f32_e32 v220, v220, v102
	v_mfma_f32_32x32x16_bf16 v[32:47], v[228:231], v[104:107], v[32:47]
	v_add_f32_e32 v220, v220, v103
	v_add_f32_e32 v220, v220, v108
	v_add_f32_e32 v220, v220, v109
	v_mfma_f32_32x32x16_bf16 v[16:31], v[232:235], v[104:107], v[16:31]
	v_add_f32_e32 v220, v220, v110
	v_add_f32_e32 v220, v220, v111
	v_mfma_f32_32x32x16_bf16 v[0:15], v[236:239], v[104:107], v[0:15]
	v_add_u32_e32 v221, v209, v203
	v_add_u32_e32 v222, v209, v204
	ds_read_b128 v[224:227], v221
	ds_read_b128 v[228:231], v221 offset:4096
	ds_read_b128 v[232:235], v222
	ds_read_b128 v[236:239], v222 offset:4096
	s_waitcnt lgkmcnt(4)
	v_mfma_f32_32x32x16_bf16 v[112:127], v[144:147], v[140:143], 0
	v_exp_f32_e32 v80, v80
	v_exp_f32_e32 v81, v81
	v_add_f32_e32 v220, v220, v80
	v_cvt_pk_bf16_f32 v240, v80, v81
	v_mfma_f32_32x32x16_bf16 v[96:111], v[148:151], v[140:143], 0
	v_exp_f32_e32 v82, v82
	v_exp_f32_e32 v83, v83
	v_add_f32_e32 v220, v220, v81
	v_cvt_pk_bf16_f32 v241, v82, v83
	v_mfma_f32_32x32x16_bf16 v[112:127], v[152:155], v[136:139], v[112:127]
	v_exp_f32_e32 v84, v84
	v_exp_f32_e32 v85, v85
	v_add_f32_e32 v220, v220, v82
	v_cvt_pk_bf16_f32 v242, v84, v85
	v_mfma_f32_32x32x16_bf16 v[96:111], v[156:159], v[136:139], v[96:111]
	v_exp_f32_e32 v86, v86
	v_exp_f32_e32 v87, v87
	v_add_f32_e32 v220, v220, v83
	v_cvt_pk_bf16_f32 v243, v86, v87
	v_add_u32_e32 v221, v208, v201
	ds_read_b128 v[144:147], v221 offset:49152
	ds_read_b128 v[148:151], v221 offset:53248
	ds_read_b128 v[152:155], v221 offset:57344
	ds_read_b128 v[156:159], v221 offset:61440
	s_waitcnt lgkmcnt(4)
	v_mfma_f32_32x32x16_bf16 v[112:127], v[224:227], v[132:135], v[112:127]
	v_exp_f32_e32 v88, v88
	v_exp_f32_e32 v89, v89
	v_add_f32_e32 v220, v220, v84
	v_cvt_pk_bf16_f32 v244, v88, v89
	v_mfma_f32_32x32x16_bf16 v[96:111], v[228:231], v[132:135], v[96:111]
	v_exp_f32_e32 v90, v90
	v_exp_f32_e32 v91, v91
	v_add_f32_e32 v220, v220, v85
	v_cvt_pk_bf16_f32 v245, v90, v91
	v_mfma_f32_32x32x16_bf16 v[112:127], v[232:235], v[128:131], v[112:127]
	v_exp_f32_e32 v92, v92
	v_exp_f32_e32 v93, v93
	v_add_f32_e32 v220, v220, v86
	v_cvt_pk_bf16_f32 v246, v92, v93
	v_mfma_f32_32x32x16_bf16 v[96:111], v[236:239], v[128:131], v[96:111]
	v_exp_f32_e32 v94, v94
	v_exp_f32_e32 v95, v95
	v_add_f32_e32 v220, v220, v87
	v_cvt_pk_bf16_f32 v247, v94, v95
	v_add_u32_e32 v221, v208, v202
	ds_read_b128 v[224:227], v221 offset:49152
	ds_read_b128 v[228:231], v221 offset:53248
	ds_read_b128 v[232:235], v221 offset:57344
	ds_read_b128 v[236:239], v221 offset:61440
	s_waitcnt lgkmcnt(4)
	v_mfma_f32_32x32x16_bf16 v[48:63], v[144:147], v[240:243], v[48:63]
	v_exp_f32_e32 v64, v64
	v_exp_f32_e32 v65, v65
	v_add_f32_e32 v220, v220, v88
	v_cvt_pk_bf16_f32 v248, v64, v65
	v_mfma_f32_32x32x16_bf16 v[32:47], v[148:151], v[240:243], v[32:47]
	v_exp_f32_e32 v66, v66
	v_exp_f32_e32 v67, v67
	v_add_f32_e32 v220, v220, v89
	v_cvt_pk_bf16_f32 v249, v66, v67
	v_mfma_f32_32x32x16_bf16 v[16:31], v[152:155], v[240:243], v[16:31]
	v_exp_f32_e32 v68, v68
	v_exp_f32_e32 v69, v69
	v_add_f32_e32 v220, v220, v90
	v_cvt_pk_bf16_f32 v250, v68, v69
	v_mfma_f32_32x32x16_bf16 v[0:15], v[156:159], v[240:243], v[0:15]
	v_exp_f32_e32 v70, v70
	v_exp_f32_e32 v71, v71
	v_add_f32_e32 v220, v220, v91
	v_cvt_pk_bf16_f32 v251, v70, v71
	v_add_u32_e32 v221, v208, v203
	ds_read_b128 v[144:147], v221 offset:49152
	ds_read_b128 v[148:151], v221 offset:53248
	ds_read_b128 v[152:155], v221 offset:57344
	ds_read_b128 v[156:159], v221 offset:61440
	s_waitcnt lgkmcnt(4)
	v_mfma_f32_32x32x16_bf16 v[48:63], v[224:227], v[244:247], v[48:63]
	s_add_i32 s17, s14, 4
	s_min_u32 s17, s17, s15
	v_exp_f32_e32 v72, v72
	v_exp_f32_e32 v73, v73
	v_add_f32_e32 v220, v220, v72
	v_add_f32_e32 v220, v220, v73
	v_mfma_f32_32x32x16_bf16 v[32:47], v[228:231], v[244:247], v[32:47]
	s_mul_i32 s18, s17, 0x30000
	s_lshl_b32 s19, s17, 7
	v_exp_f32_e32 v74, v74
	v_exp_f32_e32 v75, v75
	v_add_f32_e32 v220, v220, v74
	v_add_f32_e32 v220, v220, v75
	v_mfma_f32_32x32x16_bf16 v[16:31], v[232:235], v[244:247], v[16:31]
	s_or_b32 s98, s18, 0x80
	s_add_i32 s99, s19, 0x200000
	v_exp_f32_e32 v76, v76
	v_exp_f32_e32 v77, v77
	v_cvt_pk_bf16_f32 v72, v72, v73
	v_add_f32_e32 v220, v220, v92
	v_mfma_f32_32x32x16_bf16 v[0:15], v[236:239], v[244:247], v[0:15]
	v_exp_f32_e32 v78, v78
	v_exp_f32_e32 v79, v79
	v_cvt_pk_bf16_f32 v73, v74, v75
	v_add_f32_e32 v220, v220, v93
	v_add_u32_e32 v221, v208, v204
	ds_read_b128 v[224:227], v221 offset:49152
	ds_read_b128 v[228:231], v221 offset:53248
	ds_read_b128 v[232:235], v221 offset:57344
	ds_read_b128 v[236:239], v221 offset:61440
	s_waitcnt lgkmcnt(4)
	s_mov_b32 m0, s72
	v_mfma_f32_32x32x16_bf16 v[48:63], v[144:147], v[248:251], v[48:63]
	buffer_load_dwordx4 v205, s[28:31], s18 offen lds
	v_cvt_pk_bf16_f32 v74, v76, v77
	v_cvt_pk_bf16_f32 v75, v78, v79
	s_mov_b32 m0, s73
	v_mfma_f32_32x32x16_bf16 v[32:47], v[148:151], v[248:251], v[32:47]
	buffer_load_dwordx4 v205, s[28:31], s98 offen lds
	v_add_f32_e32 v220, v220, v94
	v_add_f32_e32 v220, v220, v95
	s_mov_b32 m0, s6
	v_mfma_f32_32x32x16_bf16 v[16:31], v[152:155], v[248:251], v[16:31]
	buffer_load_dwordx4 v206, s[36:39], s19 offen lds
	v_add_f32_e32 v220, v220, v64
	v_add_f32_e32 v220, v220, v65
	s_mov_b32 m0, s7
	v_mfma_f32_32x32x16_bf16 v[0:15], v[156:159], v[248:251], v[0:15]
	buffer_load_dwordx4 v206, s[36:39], s99 offen lds
	v_add_f32_e32 v220, v220, v66
	v_add_f32_e32 v220, v220, v67
	s_waitcnt vmcnt(4) lgkmcnt(0)
	s_barrier
	v_add_u32_e32 v221, v210, v201
	v_add_u32_e32 v222, v210, v202
	ds_read_b128 v[144:147], v221
	ds_read_b128 v[148:151], v221 offset:4096
	ds_read_b128 v[152:155], v222
	ds_read_b128 v[156:159], v222 offset:4096
	v_mfma_f32_32x32x16_bf16 v[48:63], v[224:227], v[72:75], v[48:63]
	v_add_f32_e32 v220, v220, v68
	v_add_f32_e32 v220, v220, v69
	v_add_f32_e32 v220, v220, v70
	v_mfma_f32_32x32x16_bf16 v[32:47], v[228:231], v[72:75], v[32:47]
	v_add_f32_e32 v220, v220, v71
	v_add_f32_e32 v220, v220, v76
	v_add_f32_e32 v220, v220, v77
	v_mfma_f32_32x32x16_bf16 v[16:31], v[232:235], v[72:75], v[16:31]
	v_add_f32_e32 v220, v220, v78
	v_add_f32_e32 v220, v220, v79
	v_mfma_f32_32x32x16_bf16 v[0:15], v[236:239], v[72:75], v[0:15]
	s_add_i32 s14, s14, 2
.Lat_exit:
	s_waitcnt lgkmcnt(0)
	s_mov_b32 s51, s14

	.amdhsa_kernel _Z9hymba_fwd4Args
		.amdhsa_group_segment_fixed_size 288
		.amdhsa_private_segment_fixed_size 0
		.amdhsa_kernarg_size 488
		.amdhsa_user_sgpr_count 2
		.amdhsa_user_sgpr_dispatch_ptr 0
		.amdhsa_user_sgpr_queue_ptr 0
		.amdhsa_user_sgpr_kernarg_segment_ptr 1
		.amdhsa_user_sgpr_dispatch_id 0
		.amdhsa_user_sgpr_kernarg_preload_length 0
		.amdhsa_user_sgpr_kernarg_preload_offset 0
		.amdhsa_user_sgpr_private_segment_size 0
		.amdhsa_uses_dynamic_stack 0
		.amdhsa_enable_private_segment 0
		.amdhsa_system_sgpr_workgroup_id_x 1
		.amdhsa_system_sgpr_workgroup_id_y 0
		.amdhsa_system_sgpr_workgroup_id_z 0
		.amdhsa_system_sgpr_workgroup_info 0
		.amdhsa_system_vgpr_workitem_id 2
		.amdhsa_next_free_vgpr 256
		.amdhsa_next_free_sgpr 102
		.amdhsa_accum_offset 256
		.amdhsa_reserve_vcc 1
		.amdhsa_float_round_mode_32 0
		.amdhsa_float_round_mode_16_64 0
		.amdhsa_float_denorm_mode_32 3
		.amdhsa_float_denorm_mode_16_64 3
		.amdhsa_dx10_clamp 1
		.amdhsa_ieee_mode 1
		.amdhsa_fp16_overflow 0
		.amdhsa_tg_split 0
		.amdhsa_exception_fp_ieee_invalid_op 0
		.amdhsa_exception_fp_denorm_src 0
		.amdhsa_exception_fp_ieee_div_zero 0
		.amdhsa_exception_fp_ieee_overflow 0
		.amdhsa_exception_fp_ieee_underflow 0
		.amdhsa_exception_fp_ieee_inexact 0
		.amdhsa_exception_int_div_zero 0
	.end_amdhsa_kernel

amdhsa.kernels:
  - .agpr_count:     0
    .args:
      - .offset:         0
        .size:           232
        .value_kind:     by_value
      - .offset:         232
        .size:           4
        .value_kind:     hidden_block_count_x
      - .offset:         236
        .size:           4
        .value_kind:     hidden_block_count_y
      - .offset:         240
        .size:           4
        .value_kind:     hidden_block_count_z
      - .offset:         244
        .size:           2
        .value_kind:     hidden_group_size_x
      - .offset:         246
        .size:           2
        .value_kind:     hidden_group_size_y
      - .offset:         248
        .size:           2
        .value_kind:     hidden_group_size_z
      - .offset:         250
        .size:           2
        .value_kind:     hidden_remainder_x
      - .offset:         252
        .size:           2
        .value_kind:     hidden_remainder_y
      - .offset:         254
        .size:           2
        .value_kind:     hidden_remainder_z
      - .offset:         272
        .size:           8
        .value_kind:     hidden_global_offset_x
      - .offset:         280
        .size:           8
        .value_kind:     hidden_global_offset_y
      - .offset:         288
        .size:           8
        .value_kind:     hidden_global_offset_z
      - .offset:         296
        .size:           2
        .value_kind:     hidden_grid_dims
      - .offset:         320
        .size:           8
        .value_kind:     hidden_multigrid_sync_arg
      - .offset:         352
        .size:           4
        .value_kind:     hidden_dynamic_lds_size
    .group_segment_fixed_size: 288
    .kernarg_segment_align: 8
    .kernarg_segment_size: 488
    .language:       OpenCL C
    .language_version:
      - 2
      - 0
    .max_flat_workgroup_size: 512
    .name:           _Z9hymba_fwd4Args
    .private_segment_fixed_size: 0
    .sgpr_count:     108
    .sgpr_spill_count: 85
    .symbol:         _Z9hymba_fwd4Args.kd
    .uniform_work_group_size: 1
    .uses_dynamic_stack: false
    .vgpr_count:     256
    .vgpr_spill_count: 0
    .wavefront_size: 64
